# one static s_setprio 1 at entry for workgroups 256..511 (the second workgroup on each CU) so the two co-resident workgroups drift out of lockstep
# speedup vs baseline: 1.2209x; 1.0021x over previous
; __global__ void __launch_bounds__(256, 2) fwd_megakernel(Params p) {
;   __shared__ __attribute__((aligned(256))) char smem_all[SMEM_BYTES];
;   char* smem = smem_all + 256;
;   const int bid = blockIdx.x, nb = gridDim.x;
;   const bool multi = (p.phase_hi - p.phase_lo) > 1;
;   XcdBarrier xb; xb.bar = p.bar; xb.x = 0; xb.st = (volatile unsigned*)smem_all;
;   if (multi) {
;     if (threadIdx.x == 0) { ((volatile unsigned*)smem_all)[0] = 0u; ((volatile unsigned*)smem_all)[1] = 0u; }
_Z14fwd_megakernel6Params:
	s_mov_b32 s100, s2
	s_cmpk_lt_u32 s2, 0x100
	s_cbranch_scc1 .Lmy_noprio
	s_setprio 1
.Lmy_noprio:
	s_load_dwordx16 s[40:55], s[0:1], 0x80
	s_load_dwordx4 s[12:15], s[0:1], 0x138
	s_load_dwordx2 s[8:9], s[0:1], 0x1c0
	s_load_dwordx8 s[16:23], s[0:1], 0x118
	s_load_dword s4, s[0:1], 0x1c8
	s_add_u32 s6, s0, 0x1c8
	s_addc_u32 s7, s1, 0
	s_mov_b32 s10, 0
	s_waitcnt lgkmcnt(0)
	v_writelane_b32 v253, s16, 0
	s_nop 1
	v_writelane_b32 v253, s17, 1
	v_writelane_b32 v253, s18, 2
	v_writelane_b32 v253, s19, 3
	v_writelane_b32 v253, s20, 4
	v_writelane_b32 v253, s21, 5
	v_writelane_b32 v253, s22, 6
	v_writelane_b32 v253, s23, 7
	v_writelane_b32 v253, s4, 8
	s_nop 1
	v_writelane_b32 v253, s5, 9
	v_writelane_b32 v253, s6, 10
	s_nop 1
	v_writelane_b32 v253, s7, 11
	v_writelane_b32 v253, s8, 12
	s_sub_i32 s3, s9, s8
	s_cmp_lt_i32 s3, 2
	v_writelane_b32 v253, s9, 13
	s_cbranch_scc1 .LBB0_7
	v_and_b32_e32 v1, 0x3ff, v0
	v_cmp_eq_u32_e32 vcc, 0, v1
	s_and_saveexec_b64 s[4:5], vcc
	s_cbranch_execz .LBB0_3
	s_mov_b64 s[6:7], src_shared_base
	v_mov_b32_e32 v2, 0
	v_mov_b32_e32 v3, s7
	v_mov_b32_e32 v4, 4
	v_mov_b32_e32 v5, s7
	flat_store_dword v[2:3], v2 sc0 sc1
	s_waitcnt vmcnt(0)
	flat_store_dword v[4:5], v2 sc0 sc1
	s_waitcnt vmcnt(0)
